# gates epilogue math switched to packed f32 mul/add (v_pk_mul_f32/v_pk_add_f32, bit-identical per element), rest as v76
# baseline (speedup 1.0000x reference)
.LBB0_1465:
	v_or_b32_e32 v0, 0xfffffd00, v168
	v_lshl_add_u32 v0, s20, 7, v0
	v_lshlrev_b32_e32 v0, 1, v0
	v_lshl_add_u32 v134, v156, 10, v0
	v_add_u32_e32 v135, 0x4000, v134
	v_add_u32_e32 v136, 0x8000, v134
	v_add_u32_e32 v137, 0xc000, v134
	v_add_u32_e32 v158, 0x20000, v134
	v_add_u32_e32 v159, 0x24000, v134
	v_add_u32_e32 v160, 0x28000, v134
	v_add_u32_e32 v161, 0x2c000, v134
	global_load_dwordx4 v[170:173], v134, s[8:9]
	global_load_dwordx4 v[174:177], v135, s[8:9]
	global_load_dwordx4 v[178:181], v136, s[8:9]
	global_load_dwordx4 v[182:185], v137, s[8:9]
	global_load_dwordx4 v[186:189], v158, s[8:9]
	global_load_dwordx4 v[190:193], v159, s[8:9]
	global_load_dwordx4 v[194:197], v160, s[8:9]
	global_load_dwordx4 v[198:201], v161, s[8:9]
	v_mov_b32_e32 v162, 0xbfb8aa3b
	v_mov_b32_e32 v163, 0xbfb8aa3b
	v_mov_b32_e32 v164, 1.0
	v_mov_b32_e32 v165, 1.0
	v_pk_mul_f32 v[224:225], v[126:127], v[162:163]
	v_pk_mul_f32 v[226:227], v[128:129], v[162:163]
	v_pk_mul_f32 v[228:229], v[122:123], v[162:163]
	v_pk_mul_f32 v[230:231], v[124:125], v[162:163]
	v_pk_mul_f32 v[232:233], v[118:119], v[162:163]
	v_pk_mul_f32 v[234:235], v[120:121], v[162:163]
	v_pk_mul_f32 v[236:237], v[114:115], v[162:163]
	v_pk_mul_f32 v[238:239], v[116:117], v[162:163]
	v_exp_f32_e32 v224, v224
	v_exp_f32_e32 v225, v225
	v_exp_f32_e32 v226, v226
	v_exp_f32_e32 v227, v227
	v_exp_f32_e32 v228, v228
	v_exp_f32_e32 v229, v229
	v_exp_f32_e32 v230, v230
	v_exp_f32_e32 v231, v231
	v_exp_f32_e32 v232, v232
	v_exp_f32_e32 v233, v233
	v_exp_f32_e32 v234, v234
	v_exp_f32_e32 v235, v235
	v_exp_f32_e32 v236, v236
	v_exp_f32_e32 v237, v237
	v_exp_f32_e32 v238, v238
	v_exp_f32_e32 v239, v239
	v_pk_add_f32 v[224:225], v[224:225], v[164:165]
	v_pk_add_f32 v[226:227], v[226:227], v[164:165]
	v_pk_add_f32 v[228:229], v[228:229], v[164:165]
	v_pk_add_f32 v[230:231], v[230:231], v[164:165]
	v_pk_add_f32 v[232:233], v[232:233], v[164:165]
	v_pk_add_f32 v[234:235], v[234:235], v[164:165]
	v_pk_add_f32 v[236:237], v[236:237], v[164:165]
	v_pk_add_f32 v[238:239], v[238:239], v[164:165]
	v_rcp_f32_e32 v224, v224
	v_rcp_f32_e32 v225, v225
	v_rcp_f32_e32 v226, v226
	v_rcp_f32_e32 v227, v227
	v_rcp_f32_e32 v228, v228
	v_rcp_f32_e32 v229, v229
	v_rcp_f32_e32 v230, v230
	v_rcp_f32_e32 v231, v231
	v_rcp_f32_e32 v232, v232
	v_rcp_f32_e32 v233, v233
	v_rcp_f32_e32 v234, v234
	v_rcp_f32_e32 v235, v235
	v_rcp_f32_e32 v236, v236
	v_rcp_f32_e32 v237, v237
	v_rcp_f32_e32 v238, v238
	v_rcp_f32_e32 v239, v239
	v_pk_mul_f32 v[118:119], v[118:119], v[232:233]
	v_pk_mul_f32 v[120:121], v[120:121], v[234:235]
	v_pk_mul_f32 v[114:115], v[114:115], v[236:237]
	v_pk_mul_f32 v[116:117], v[116:117], v[238:239]
	s_waitcnt vmcnt(7)
	v_lshlrev_b32_e32 v232, 16, v170
	v_and_b32_e32 v233, 0xffff0000, v170
	v_lshlrev_b32_e32 v234, 16, v171
	v_and_b32_e32 v235, 0xffff0000, v171
	v_lshlrev_b32_e32 v236, 16, v172
	v_and_b32_e32 v237, 0xffff0000, v172
	v_lshlrev_b32_e32 v238, 16, v173
	v_and_b32_e32 v239, 0xffff0000, v173
	v_pk_mul_f32 v[224:225], v[224:225], v[232:233]
	v_pk_mul_f32 v[226:227], v[226:227], v[234:235]
	v_pk_mul_f32 v[228:229], v[228:229], v[236:237]
	v_pk_mul_f32 v[230:231], v[230:231], v[238:239]
	v_pk_mul_f32 v[118:119], v[118:119], v[224:225]
	v_pk_mul_f32 v[120:121], v[120:121], v[226:227]
	v_pk_mul_f32 v[114:115], v[114:115], v[228:229]
	v_pk_mul_f32 v[116:117], v[116:117], v[230:231]
	v_cvt_pk_bf16_f32 v170, v118, v119
	v_cvt_pk_bf16_f32 v171, v120, v121
	v_cvt_pk_bf16_f32 v172, v114, v115
	v_cvt_pk_bf16_f32 v173, v116, v117
	s_nop 1
	global_store_dwordx4 v134, v[170:173], s[8:9]
	v_pk_mul_f32 v[224:225], v[110:111], v[162:163]
	v_pk_mul_f32 v[226:227], v[112:113], v[162:163]
	v_pk_mul_f32 v[228:229], v[106:107], v[162:163]
	v_pk_mul_f32 v[230:231], v[108:109], v[162:163]
	v_pk_mul_f32 v[232:233], v[102:103], v[162:163]
	v_pk_mul_f32 v[234:235], v[104:105], v[162:163]
	v_pk_mul_f32 v[236:237], v[98:99], v[162:163]
	v_pk_mul_f32 v[238:239], v[100:101], v[162:163]
	v_exp_f32_e32 v224, v224
	v_exp_f32_e32 v225, v225
	v_exp_f32_e32 v226, v226
	v_exp_f32_e32 v227, v227
	v_exp_f32_e32 v228, v228
	v_exp_f32_e32 v229, v229
	v_exp_f32_e32 v230, v230
	v_exp_f32_e32 v231, v231
	v_exp_f32_e32 v232, v232
	v_exp_f32_e32 v233, v233
	v_exp_f32_e32 v234, v234
	v_exp_f32_e32 v235, v235
	v_exp_f32_e32 v236, v236
	v_exp_f32_e32 v237, v237
	v_exp_f32_e32 v238, v238
	v_exp_f32_e32 v239, v239
	v_pk_add_f32 v[224:225], v[224:225], v[164:165]
	v_pk_add_f32 v[226:227], v[226:227], v[164:165]
	v_pk_add_f32 v[228:229], v[228:229], v[164:165]
	v_pk_add_f32 v[230:231], v[230:231], v[164:165]
	v_pk_add_f32 v[232:233], v[232:233], v[164:165]
	v_pk_add_f32 v[234:235], v[234:235], v[164:165]
	v_pk_add_f32 v[236:237], v[236:237], v[164:165]
	v_pk_add_f32 v[238:239], v[238:239], v[164:165]
	v_rcp_f32_e32 v224, v224
	v_rcp_f32_e32 v225, v225
	v_rcp_f32_e32 v226, v226
	v_rcp_f32_e32 v227, v227
	v_rcp_f32_e32 v228, v228
	v_rcp_f32_e32 v229, v229
	v_rcp_f32_e32 v230, v230
	v_rcp_f32_e32 v231, v231
	v_rcp_f32_e32 v232, v232
	v_rcp_f32_e32 v233, v233
	v_rcp_f32_e32 v234, v234
	v_rcp_f32_e32 v235, v235
	v_rcp_f32_e32 v236, v236
	v_rcp_f32_e32 v237, v237
	v_rcp_f32_e32 v238, v238
	v_rcp_f32_e32 v239, v239
	v_pk_mul_f32 v[102:103], v[102:103], v[232:233]
	v_pk_mul_f32 v[104:105], v[104:105], v[234:235]
	v_pk_mul_f32 v[98:99], v[98:99], v[236:237]
	v_pk_mul_f32 v[100:101], v[100:101], v[238:239]
	s_waitcnt vmcnt(7)
	v_lshlrev_b32_e32 v232, 16, v174
	v_and_b32_e32 v233, 0xffff0000, v174
	v_lshlrev_b32_e32 v234, 16, v175
	v_and_b32_e32 v235, 0xffff0000, v175
	v_lshlrev_b32_e32 v236, 16, v176
	v_and_b32_e32 v237, 0xffff0000, v176
	v_lshlrev_b32_e32 v238, 16, v177
	v_and_b32_e32 v239, 0xffff0000, v177
	v_pk_mul_f32 v[224:225], v[224:225], v[232:233]
	v_pk_mul_f32 v[226:227], v[226:227], v[234:235]
	v_pk_mul_f32 v[228:229], v[228:229], v[236:237]
	v_pk_mul_f32 v[230:231], v[230:231], v[238:239]
	v_pk_mul_f32 v[102:103], v[102:103], v[224:225]
	v_pk_mul_f32 v[104:105], v[104:105], v[226:227]
	v_pk_mul_f32 v[98:99], v[98:99], v[228:229]
	v_pk_mul_f32 v[100:101], v[100:101], v[230:231]
	v_cvt_pk_bf16_f32 v174, v102, v103
	v_cvt_pk_bf16_f32 v175, v104, v105
	v_cvt_pk_bf16_f32 v176, v98, v99
	v_cvt_pk_bf16_f32 v177, v100, v101
	s_nop 1
	global_store_dwordx4 v135, v[174:177], s[8:9]
	v_pk_mul_f32 v[224:225], v[94:95], v[162:163]
	v_pk_mul_f32 v[226:227], v[96:97], v[162:163]
	v_pk_mul_f32 v[228:229], v[90:91], v[162:163]
	v_pk_mul_f32 v[230:231], v[92:93], v[162:163]
	v_pk_mul_f32 v[232:233], v[86:87], v[162:163]
	v_pk_mul_f32 v[234:235], v[88:89], v[162:163]
	v_pk_mul_f32 v[236:237], v[82:83], v[162:163]
	v_pk_mul_f32 v[238:239], v[84:85], v[162:163]
	v_exp_f32_e32 v224, v224
	v_exp_f32_e32 v225, v225
	v_exp_f32_e32 v226, v226
	v_exp_f32_e32 v227, v227
	v_exp_f32_e32 v228, v228
	v_exp_f32_e32 v229, v229
	v_exp_f32_e32 v230, v230
	v_exp_f32_e32 v231, v231
	v_exp_f32_e32 v232, v232
	v_exp_f32_e32 v233, v233
	v_exp_f32_e32 v234, v234
	v_exp_f32_e32 v235, v235
	v_exp_f32_e32 v236, v236
	v_exp_f32_e32 v237, v237
	v_exp_f32_e32 v238, v238
	v_exp_f32_e32 v239, v239
	v_pk_add_f32 v[224:225], v[224:225], v[164:165]
	v_pk_add_f32 v[226:227], v[226:227], v[164:165]
	v_pk_add_f32 v[228:229], v[228:229], v[164:165]
	v_pk_add_f32 v[230:231], v[230:231], v[164:165]
	v_pk_add_f32 v[232:233], v[232:233], v[164:165]
	v_pk_add_f32 v[234:235], v[234:235], v[164:165]
	v_pk_add_f32 v[236:237], v[236:237], v[164:165]
	v_pk_add_f32 v[238:239], v[238:239], v[164:165]
	v_rcp_f32_e32 v224, v224
	v_rcp_f32_e32 v225, v225
	v_rcp_f32_e32 v226, v226
	v_rcp_f32_e32 v227, v227
	v_rcp_f32_e32 v228, v228
	v_rcp_f32_e32 v229, v229
	v_rcp_f32_e32 v230, v230
	v_rcp_f32_e32 v231, v231
	v_rcp_f32_e32 v232, v232
	v_rcp_f32_e32 v233, v233
	v_rcp_f32_e32 v234, v234
	v_rcp_f32_e32 v235, v235
	v_rcp_f32_e32 v236, v236
	v_rcp_f32_e32 v237, v237
	v_rcp_f32_e32 v238, v238
	v_rcp_f32_e32 v239, v239
	v_pk_mul_f32 v[86:87], v[86:87], v[232:233]
	v_pk_mul_f32 v[88:89], v[88:89], v[234:235]
	v_pk_mul_f32 v[82:83], v[82:83], v[236:237]
	v_pk_mul_f32 v[84:85], v[84:85], v[238:239]
	s_waitcnt vmcnt(7)
	v_lshlrev_b32_e32 v232, 16, v178
	v_and_b32_e32 v233, 0xffff0000, v178
	v_lshlrev_b32_e32 v234, 16, v179
	v_and_b32_e32 v235, 0xffff0000, v179
	v_lshlrev_b32_e32 v236, 16, v180
	v_and_b32_e32 v237, 0xffff0000, v180
	v_lshlrev_b32_e32 v238, 16, v181
	v_and_b32_e32 v239, 0xffff0000, v181
	v_pk_mul_f32 v[224:225], v[224:225], v[232:233]
	v_pk_mul_f32 v[226:227], v[226:227], v[234:235]
	v_pk_mul_f32 v[228:229], v[228:229], v[236:237]
	v_pk_mul_f32 v[230:231], v[230:231], v[238:239]
	v_pk_mul_f32 v[86:87], v[86:87], v[224:225]
	v_pk_mul_f32 v[88:89], v[88:89], v[226:227]
	v_pk_mul_f32 v[82:83], v[82:83], v[228:229]
	v_pk_mul_f32 v[84:85], v[84:85], v[230:231]
	v_cvt_pk_bf16_f32 v178, v86, v87
	v_cvt_pk_bf16_f32 v179, v88, v89
	v_cvt_pk_bf16_f32 v180, v82, v83
	v_cvt_pk_bf16_f32 v181, v84, v85
	s_nop 1
	global_store_dwordx4 v136, v[178:181], s[8:9]
	v_pk_mul_f32 v[224:225], v[78:79], v[162:163]
	v_pk_mul_f32 v[226:227], v[80:81], v[162:163]
	v_pk_mul_f32 v[228:229], v[74:75], v[162:163]
	v_pk_mul_f32 v[230:231], v[76:77], v[162:163]
	v_pk_mul_f32 v[232:233], v[70:71], v[162:163]
	v_pk_mul_f32 v[234:235], v[72:73], v[162:163]
	v_pk_mul_f32 v[236:237], v[66:67], v[162:163]
	v_pk_mul_f32 v[238:239], v[68:69], v[162:163]
	v_exp_f32_e32 v224, v224
	v_exp_f32_e32 v225, v225
	v_exp_f32_e32 v226, v226
	v_exp_f32_e32 v227, v227
	v_exp_f32_e32 v228, v228
	v_exp_f32_e32 v229, v229
	v_exp_f32_e32 v230, v230
	v_exp_f32_e32 v231, v231
	v_exp_f32_e32 v232, v232
	v_exp_f32_e32 v233, v233
	v_exp_f32_e32 v234, v234
	v_exp_f32_e32 v235, v235
	v_exp_f32_e32 v236, v236
	v_exp_f32_e32 v237, v237
	v_exp_f32_e32 v238, v238
	v_exp_f32_e32 v239, v239
	v_pk_add_f32 v[224:225], v[224:225], v[164:165]
	v_pk_add_f32 v[226:227], v[226:227], v[164:165]
	v_pk_add_f32 v[228:229], v[228:229], v[164:165]
	v_pk_add_f32 v[230:231], v[230:231], v[164:165]
	v_pk_add_f32 v[232:233], v[232:233], v[164:165]
	v_pk_add_f32 v[234:235], v[234:235], v[164:165]
	v_pk_add_f32 v[236:237], v[236:237], v[164:165]
	v_pk_add_f32 v[238:239], v[238:239], v[164:165]
	v_rcp_f32_e32 v224, v224
	v_rcp_f32_e32 v225, v225
	v_rcp_f32_e32 v226, v226
	v_rcp_f32_e32 v227, v227
	v_rcp_f32_e32 v228, v228
	v_rcp_f32_e32 v229, v229
	v_rcp_f32_e32 v230, v230
	v_rcp_f32_e32 v231, v231
	v_rcp_f32_e32 v232, v232
	v_rcp_f32_e32 v233, v233
	v_rcp_f32_e32 v234, v234
	v_rcp_f32_e32 v235, v235
	v_rcp_f32_e32 v236, v236
	v_rcp_f32_e32 v237, v237
	v_rcp_f32_e32 v238, v238
	v_rcp_f32_e32 v239, v239
	v_pk_mul_f32 v[70:71], v[70:71], v[232:233]
	v_pk_mul_f32 v[72:73], v[72:73], v[234:235]
	v_pk_mul_f32 v[66:67], v[66:67], v[236:237]
	v_pk_mul_f32 v[68:69], v[68:69], v[238:239]
	s_waitcnt vmcnt(7)
	v_lshlrev_b32_e32 v232, 16, v182
	v_and_b32_e32 v233, 0xffff0000, v182
	v_lshlrev_b32_e32 v234, 16, v183
	v_and_b32_e32 v235, 0xffff0000, v183
	v_lshlrev_b32_e32 v236, 16, v184
	v_and_b32_e32 v237, 0xffff0000, v184
	v_lshlrev_b32_e32 v238, 16, v185
	v_and_b32_e32 v239, 0xffff0000, v185
	v_pk_mul_f32 v[224:225], v[224:225], v[232:233]
	v_pk_mul_f32 v[226:227], v[226:227], v[234:235]
	v_pk_mul_f32 v[228:229], v[228:229], v[236:237]
	v_pk_mul_f32 v[230:231], v[230:231], v[238:239]
	v_pk_mul_f32 v[70:71], v[70:71], v[224:225]
	v_pk_mul_f32 v[72:73], v[72:73], v[226:227]
	v_pk_mul_f32 v[66:67], v[66:67], v[228:229]
	v_pk_mul_f32 v[68:69], v[68:69], v[230:231]
	v_cvt_pk_bf16_f32 v182, v70, v71
	v_cvt_pk_bf16_f32 v183, v72, v73
	v_cvt_pk_bf16_f32 v184, v66, v67
	v_cvt_pk_bf16_f32 v185, v68, v69
	s_nop 1
	global_store_dwordx4 v137, v[182:185], s[8:9]
	v_pk_mul_f32 v[224:225], v[62:63], v[162:163]
	v_pk_mul_f32 v[226:227], v[64:65], v[162:163]
	v_pk_mul_f32 v[228:229], v[58:59], v[162:163]
	v_pk_mul_f32 v[230:231], v[60:61], v[162:163]
	v_pk_mul_f32 v[232:233], v[54:55], v[162:163]
	v_pk_mul_f32 v[234:235], v[56:57], v[162:163]
	v_pk_mul_f32 v[236:237], v[50:51], v[162:163]
	v_pk_mul_f32 v[238:239], v[52:53], v[162:163]
	v_exp_f32_e32 v224, v224
	v_exp_f32_e32 v225, v225
	v_exp_f32_e32 v226, v226
	v_exp_f32_e32 v227, v227
	v_exp_f32_e32 v228, v228
	v_exp_f32_e32 v229, v229
	v_exp_f32_e32 v230, v230
	v_exp_f32_e32 v231, v231
	v_exp_f32_e32 v232, v232
	v_exp_f32_e32 v233, v233
	v_exp_f32_e32 v234, v234
	v_exp_f32_e32 v235, v235
	v_exp_f32_e32 v236, v236
	v_exp_f32_e32 v237, v237
	v_exp_f32_e32 v238, v238
	v_exp_f32_e32 v239, v239
	v_pk_add_f32 v[224:225], v[224:225], v[164:165]
	v_pk_add_f32 v[226:227], v[226:227], v[164:165]
	v_pk_add_f32 v[228:229], v[228:229], v[164:165]
	v_pk_add_f32 v[230:231], v[230:231], v[164:165]
	v_pk_add_f32 v[232:233], v[232:233], v[164:165]
	v_pk_add_f32 v[234:235], v[234:235], v[164:165]
	v_pk_add_f32 v[236:237], v[236:237], v[164:165]
	v_pk_add_f32 v[238:239], v[238:239], v[164:165]
	v_rcp_f32_e32 v224, v224
	v_rcp_f32_e32 v225, v225
	v_rcp_f32_e32 v226, v226
	v_rcp_f32_e32 v227, v227
	v_rcp_f32_e32 v228, v228
	v_rcp_f32_e32 v229, v229
	v_rcp_f32_e32 v230, v230
	v_rcp_f32_e32 v231, v231
	v_rcp_f32_e32 v232, v232
	v_rcp_f32_e32 v233, v233
	v_rcp_f32_e32 v234, v234
	v_rcp_f32_e32 v235, v235
	v_rcp_f32_e32 v236, v236
	v_rcp_f32_e32 v237, v237
	v_rcp_f32_e32 v238, v238
	v_rcp_f32_e32 v239, v239
	v_pk_mul_f32 v[54:55], v[54:55], v[232:233]
	v_pk_mul_f32 v[56:57], v[56:57], v[234:235]
	v_pk_mul_f32 v[50:51], v[50:51], v[236:237]
	v_pk_mul_f32 v[52:53], v[52:53], v[238:239]
	s_waitcnt vmcnt(7)
	v_lshlrev_b32_e32 v232, 16, v186
	v_and_b32_e32 v233, 0xffff0000, v186
	v_lshlrev_b32_e32 v234, 16, v187
	v_and_b32_e32 v235, 0xffff0000, v187
	v_lshlrev_b32_e32 v236, 16, v188
	v_and_b32_e32 v237, 0xffff0000, v188
	v_lshlrev_b32_e32 v238, 16, v189
	v_and_b32_e32 v239, 0xffff0000, v189
	v_pk_mul_f32 v[224:225], v[224:225], v[232:233]
	v_pk_mul_f32 v[226:227], v[226:227], v[234:235]
	v_pk_mul_f32 v[228:229], v[228:229], v[236:237]
	v_pk_mul_f32 v[230:231], v[230:231], v[238:239]
	v_pk_mul_f32 v[54:55], v[54:55], v[224:225]
	v_pk_mul_f32 v[56:57], v[56:57], v[226:227]
	v_pk_mul_f32 v[50:51], v[50:51], v[228:229]
	v_pk_mul_f32 v[52:53], v[52:53], v[230:231]
	v_cvt_pk_bf16_f32 v186, v54, v55
	v_cvt_pk_bf16_f32 v187, v56, v57
	v_cvt_pk_bf16_f32 v188, v50, v51
	v_cvt_pk_bf16_f32 v189, v52, v53
	s_nop 1
	global_store_dwordx4 v158, v[186:189], s[8:9]
	v_pk_mul_f32 v[224:225], v[46:47], v[162:163]
	v_pk_mul_f32 v[226:227], v[48:49], v[162:163]
	v_pk_mul_f32 v[228:229], v[42:43], v[162:163]
	v_pk_mul_f32 v[230:231], v[44:45], v[162:163]
	v_pk_mul_f32 v[232:233], v[38:39], v[162:163]
	v_pk_mul_f32 v[234:235], v[40:41], v[162:163]
	v_pk_mul_f32 v[236:237], v[34:35], v[162:163]
	v_pk_mul_f32 v[238:239], v[36:37], v[162:163]
	v_exp_f32_e32 v224, v224
	v_exp_f32_e32 v225, v225
	v_exp_f32_e32 v226, v226
	v_exp_f32_e32 v227, v227
	v_exp_f32_e32 v228, v228
	v_exp_f32_e32 v229, v229
	v_exp_f32_e32 v230, v230
	v_exp_f32_e32 v231, v231
	v_exp_f32_e32 v232, v232
	v_exp_f32_e32 v233, v233
	v_exp_f32_e32 v234, v234
	v_exp_f32_e32 v235, v235
	v_exp_f32_e32 v236, v236
	v_exp_f32_e32 v237, v237
	v_exp_f32_e32 v238, v238
	v_exp_f32_e32 v239, v239
	v_pk_add_f32 v[224:225], v[224:225], v[164:165]
	v_pk_add_f32 v[226:227], v[226:227], v[164:165]
	v_pk_add_f32 v[228:229], v[228:229], v[164:165]
	v_pk_add_f32 v[230:231], v[230:231], v[164:165]
	v_pk_add_f32 v[232:233], v[232:233], v[164:165]
	v_pk_add_f32 v[234:235], v[234:235], v[164:165]
	v_pk_add_f32 v[236:237], v[236:237], v[164:165]
	v_pk_add_f32 v[238:239], v[238:239], v[164:165]
	v_rcp_f32_e32 v224, v224
	v_rcp_f32_e32 v225, v225
	v_rcp_f32_e32 v226, v226
	v_rcp_f32_e32 v227, v227
	v_rcp_f32_e32 v228, v228
	v_rcp_f32_e32 v229, v229
	v_rcp_f32_e32 v230, v230
	v_rcp_f32_e32 v231, v231
	v_rcp_f32_e32 v232, v232
	v_rcp_f32_e32 v233, v233
	v_rcp_f32_e32 v234, v234
	v_rcp_f32_e32 v235, v235
	v_rcp_f32_e32 v236, v236
	v_rcp_f32_e32 v237, v237
	v_rcp_f32_e32 v238, v238
	v_rcp_f32_e32 v239, v239
	v_pk_mul_f32 v[38:39], v[38:39], v[232:233]
	v_pk_mul_f32 v[40:41], v[40:41], v[234:235]
	v_pk_mul_f32 v[34:35], v[34:35], v[236:237]
	v_pk_mul_f32 v[36:37], v[36:37], v[238:239]
	s_waitcnt vmcnt(7)
	v_lshlrev_b32_e32 v232, 16, v190
	v_and_b32_e32 v233, 0xffff0000, v190
	v_lshlrev_b32_e32 v234, 16, v191
	v_and_b32_e32 v235, 0xffff0000, v191
	v_lshlrev_b32_e32 v236, 16, v192
	v_and_b32_e32 v237, 0xffff0000, v192
	v_lshlrev_b32_e32 v238, 16, v193
	v_and_b32_e32 v239, 0xffff0000, v193
	v_pk_mul_f32 v[224:225], v[224:225], v[232:233]
	v_pk_mul_f32 v[226:227], v[226:227], v[234:235]
	v_pk_mul_f32 v[228:229], v[228:229], v[236:237]
	v_pk_mul_f32 v[230:231], v[230:231], v[238:239]
	v_pk_mul_f32 v[38:39], v[38:39], v[224:225]
	v_pk_mul_f32 v[40:41], v[40:41], v[226:227]
	v_pk_mul_f32 v[34:35], v[34:35], v[228:229]
	v_pk_mul_f32 v[36:37], v[36:37], v[230:231]
	v_cvt_pk_bf16_f32 v190, v38, v39
	v_cvt_pk_bf16_f32 v191, v40, v41
	v_cvt_pk_bf16_f32 v192, v34, v35
	v_cvt_pk_bf16_f32 v193, v36, v37
	s_nop 1
	global_store_dwordx4 v159, v[190:193], s[8:9]
	v_pk_mul_f32 v[224:225], v[30:31], v[162:163]
	v_pk_mul_f32 v[226:227], v[32:33], v[162:163]
	v_pk_mul_f32 v[228:229], v[26:27], v[162:163]
	v_pk_mul_f32 v[230:231], v[28:29], v[162:163]
	v_pk_mul_f32 v[232:233], v[22:23], v[162:163]
	v_pk_mul_f32 v[234:235], v[24:25], v[162:163]
	v_pk_mul_f32 v[236:237], v[18:19], v[162:163]
	v_pk_mul_f32 v[238:239], v[20:21], v[162:163]
	v_exp_f32_e32 v224, v224
	v_exp_f32_e32 v225, v225
	v_exp_f32_e32 v226, v226
	v_exp_f32_e32 v227, v227
	v_exp_f32_e32 v228, v228
	v_exp_f32_e32 v229, v229
	v_exp_f32_e32 v230, v230
	v_exp_f32_e32 v231, v231
	v_exp_f32_e32 v232, v232
	v_exp_f32_e32 v233, v233
	v_exp_f32_e32 v234, v234
	v_exp_f32_e32 v235, v235
	v_exp_f32_e32 v236, v236
	v_exp_f32_e32 v237, v237
	v_exp_f32_e32 v238, v238
	v_exp_f32_e32 v239, v239
	v_pk_add_f32 v[224:225], v[224:225], v[164:165]
	v_pk_add_f32 v[226:227], v[226:227], v[164:165]
	v_pk_add_f32 v[228:229], v[228:229], v[164:165]
	v_pk_add_f32 v[230:231], v[230:231], v[164:165]
	v_pk_add_f32 v[232:233], v[232:233], v[164:165]
	v_pk_add_f32 v[234:235], v[234:235], v[164:165]
	v_pk_add_f32 v[236:237], v[236:237], v[164:165]
	v_pk_add_f32 v[238:239], v[238:239], v[164:165]
	v_rcp_f32_e32 v224, v224
	v_rcp_f32_e32 v225, v225
	v_rcp_f32_e32 v226, v226
	v_rcp_f32_e32 v227, v227
	v_rcp_f32_e32 v228, v228
	v_rcp_f32_e32 v229, v229
	v_rcp_f32_e32 v230, v230
	v_rcp_f32_e32 v231, v231
	v_rcp_f32_e32 v232, v232
	v_rcp_f32_e32 v233, v233
	v_rcp_f32_e32 v234, v234
	v_rcp_f32_e32 v235, v235
	v_rcp_f32_e32 v236, v236
	v_rcp_f32_e32 v237, v237
	v_rcp_f32_e32 v238, v238
	v_rcp_f32_e32 v239, v239
	v_pk_mul_f32 v[22:23], v[22:23], v[232:233]
	v_pk_mul_f32 v[24:25], v[24:25], v[234:235]
	v_pk_mul_f32 v[18:19], v[18:19], v[236:237]
	v_pk_mul_f32 v[20:21], v[20:21], v[238:239]
	s_waitcnt vmcnt(7)
	v_lshlrev_b32_e32 v232, 16, v194
	v_and_b32_e32 v233, 0xffff0000, v194
	v_lshlrev_b32_e32 v234, 16, v195
	v_and_b32_e32 v235, 0xffff0000, v195
	v_lshlrev_b32_e32 v236, 16, v196
	v_and_b32_e32 v237, 0xffff0000, v196
	v_lshlrev_b32_e32 v238, 16, v197
	v_and_b32_e32 v239, 0xffff0000, v197
	v_pk_mul_f32 v[224:225], v[224:225], v[232:233]
	v_pk_mul_f32 v[226:227], v[226:227], v[234:235]
	v_pk_mul_f32 v[228:229], v[228:229], v[236:237]
	v_pk_mul_f32 v[230:231], v[230:231], v[238:239]
	v_pk_mul_f32 v[22:23], v[22:23], v[224:225]
	v_pk_mul_f32 v[24:25], v[24:25], v[226:227]
	v_pk_mul_f32 v[18:19], v[18:19], v[228:229]
	v_pk_mul_f32 v[20:21], v[20:21], v[230:231]
	v_cvt_pk_bf16_f32 v194, v22, v23
	v_cvt_pk_bf16_f32 v195, v24, v25
	v_cvt_pk_bf16_f32 v196, v18, v19
	v_cvt_pk_bf16_f32 v197, v20, v21
	s_nop 1
	global_store_dwordx4 v160, v[194:197], s[8:9]
	v_pk_mul_f32 v[224:225], v[14:15], v[162:163]
	v_pk_mul_f32 v[226:227], v[16:17], v[162:163]
	v_pk_mul_f32 v[228:229], v[10:11], v[162:163]
	v_pk_mul_f32 v[230:231], v[12:13], v[162:163]
	v_pk_mul_f32 v[232:233], v[6:7], v[162:163]
	v_pk_mul_f32 v[234:235], v[8:9], v[162:163]
	v_pk_mul_f32 v[236:237], v[2:3], v[162:163]
	v_pk_mul_f32 v[238:239], v[4:5], v[162:163]
	v_exp_f32_e32 v224, v224
	v_exp_f32_e32 v225, v225
	v_exp_f32_e32 v226, v226
	v_exp_f32_e32 v227, v227
	v_exp_f32_e32 v228, v228
	v_exp_f32_e32 v229, v229
	v_exp_f32_e32 v230, v230
	v_exp_f32_e32 v231, v231
	v_exp_f32_e32 v232, v232
	v_exp_f32_e32 v233, v233
	v_exp_f32_e32 v234, v234
	v_exp_f32_e32 v235, v235
	v_exp_f32_e32 v236, v236
	v_exp_f32_e32 v237, v237
	v_exp_f32_e32 v238, v238
	v_exp_f32_e32 v239, v239
	v_pk_add_f32 v[224:225], v[224:225], v[164:165]
	v_pk_add_f32 v[226:227], v[226:227], v[164:165]
	v_pk_add_f32 v[228:229], v[228:229], v[164:165]
	v_pk_add_f32 v[230:231], v[230:231], v[164:165]
	v_pk_add_f32 v[232:233], v[232:233], v[164:165]
	v_pk_add_f32 v[234:235], v[234:235], v[164:165]
	v_pk_add_f32 v[236:237], v[236:237], v[164:165]
	v_pk_add_f32 v[238:239], v[238:239], v[164:165]
	v_rcp_f32_e32 v224, v224
	v_rcp_f32_e32 v225, v225
	v_rcp_f32_e32 v226, v226
	v_rcp_f32_e32 v227, v227
	v_rcp_f32_e32 v228, v228
	v_rcp_f32_e32 v229, v229
	v_rcp_f32_e32 v230, v230
	v_rcp_f32_e32 v231, v231
	v_rcp_f32_e32 v232, v232
	v_rcp_f32_e32 v233, v233
	v_rcp_f32_e32 v234, v234
	v_rcp_f32_e32 v235, v235
	v_rcp_f32_e32 v236, v236
	v_rcp_f32_e32 v237, v237
	v_rcp_f32_e32 v238, v238
	v_rcp_f32_e32 v239, v239
	v_pk_mul_f32 v[6:7], v[6:7], v[232:233]
	v_pk_mul_f32 v[8:9], v[8:9], v[234:235]
	v_pk_mul_f32 v[2:3], v[2:3], v[236:237]
	v_pk_mul_f32 v[4:5], v[4:5], v[238:239]
	s_waitcnt vmcnt(7)
	v_lshlrev_b32_e32 v232, 16, v198
	v_and_b32_e32 v233, 0xffff0000, v198
	v_lshlrev_b32_e32 v234, 16, v199
	v_and_b32_e32 v235, 0xffff0000, v199
	v_lshlrev_b32_e32 v236, 16, v200
	v_and_b32_e32 v237, 0xffff0000, v200
	v_lshlrev_b32_e32 v238, 16, v201
	v_and_b32_e32 v239, 0xffff0000, v201
	v_pk_mul_f32 v[224:225], v[224:225], v[232:233]
	v_pk_mul_f32 v[226:227], v[226:227], v[234:235]
	v_pk_mul_f32 v[228:229], v[228:229], v[236:237]
	v_pk_mul_f32 v[230:231], v[230:231], v[238:239]
	v_pk_mul_f32 v[6:7], v[6:7], v[224:225]
	v_pk_mul_f32 v[8:9], v[8:9], v[226:227]
	v_pk_mul_f32 v[2:3], v[2:3], v[228:229]
	v_pk_mul_f32 v[4:5], v[4:5], v[230:231]
	v_cvt_pk_bf16_f32 v198, v6, v7
	v_cvt_pk_bf16_f32 v199, v8, v9
	v_cvt_pk_bf16_f32 v200, v2, v3
	v_cvt_pk_bf16_f32 v201, v4, v5
	s_nop 1
	global_store_dwordx4 v161, v[198:201], s[8:9]
	s_branch .LBB0_1464
.LBB0_1466:
	s_lshl_b32 s13, s20, 8
	s_ashr_i32 s11, s20, 1
	s_and_b32 s13, s13, 0x100
	v_or_b32_e32 v0, s13, v168
	s_mul_hi_i32 s13, s11, 0x1200000
	s_mul_i32 s11, s11, 0x1200000
	s_add_u32 s26, s78, s11
	s_addc_u32 s27, s79, s13
	v_lshlrev_b32_e32 v0, 1, v0
	v_lshl_add_u32 v134, v156, 10, v0
	v_add_u32_e32 v135, 0x4000, v134
	v_add_u32_e32 v136, 0x8000, v134
	v_add_u32_e32 v137, 0xc000, v134
	v_add_u32_e32 v158, 0x20000, v134
	v_add_u32_e32 v159, 0x24000, v134
	v_add_u32_e32 v160, 0x28000, v134
	v_add_u32_e32 v161, 0x2c000, v134
	global_load_dwordx4 v[170:173], v134, s[26:27]
	global_load_dwordx4 v[174:177], v134, s[26:27] offset:256
	global_load_dwordx4 v[178:181], v135, s[26:27]
	global_load_dwordx4 v[182:185], v135, s[26:27] offset:256
	global_load_dwordx4 v[186:189], v136, s[26:27]
	global_load_dwordx4 v[190:193], v136, s[26:27] offset:256
	global_load_dwordx4 v[194:197], v137, s[26:27]
	global_load_dwordx4 v[198:201], v137, s[26:27] offset:256
	global_load_dwordx4 v[202:205], v158, s[26:27]
	global_load_dwordx4 v[206:209], v158, s[26:27] offset:256
	global_load_dwordx4 v[224:227], v159, s[26:27]
	global_load_dwordx4 v[228:231], v159, s[26:27] offset:256
	global_load_dwordx4 v[232:235], v160, s[26:27]
	global_load_dwordx4 v[236:239], v160, s[26:27] offset:256
	global_load_dwordx4 v[240:243], v161, s[26:27]
	global_load_dwordx4 v[244:247], v161, s[26:27] offset:256
	v_mov_b32_e32 v162, 0xbfb8aa3b
	v_mov_b32_e32 v163, 0xbfb8aa3b
	v_mov_b32_e32 v164, 1.0
	v_mov_b32_e32 v165, 1.0
	v_pk_mul_f32 v[150:151], v[126:127], v[162:163]
	v_pk_mul_f32 v[152:153], v[128:129], v[162:163]
	v_pk_mul_f32 v[154:155], v[122:123], v[162:163]
	v_pk_mul_f32 v[156:157], v[124:125], v[162:163]
	v_exp_f32_e32 v150, v150
	v_exp_f32_e32 v151, v151
	v_exp_f32_e32 v152, v152
	v_exp_f32_e32 v153, v153
	v_exp_f32_e32 v154, v154
	v_exp_f32_e32 v155, v155
	v_exp_f32_e32 v156, v156
	v_exp_f32_e32 v157, v157
	v_pk_add_f32 v[150:151], v[150:151], v[164:165]
	v_pk_add_f32 v[152:153], v[152:153], v[164:165]
	v_pk_add_f32 v[154:155], v[154:155], v[164:165]
	v_pk_add_f32 v[156:157], v[156:157], v[164:165]
	v_rcp_f32_e32 v150, v150
	v_rcp_f32_e32 v151, v151
	v_rcp_f32_e32 v152, v152
	v_rcp_f32_e32 v153, v153
	v_rcp_f32_e32 v154, v154
	v_rcp_f32_e32 v155, v155
	v_rcp_f32_e32 v156, v156
	v_rcp_f32_e32 v157, v157
	v_pk_mul_f32 v[126:127], v[126:127], v[150:151]
	v_pk_mul_f32 v[128:129], v[128:129], v[152:153]
	v_pk_mul_f32 v[122:123], v[122:123], v[154:155]
	v_pk_mul_f32 v[124:125], v[124:125], v[156:157]
	s_waitcnt vmcnt(15)
	v_lshlrev_b32_e32 v150, 16, v170
	v_and_b32_e32 v151, 0xffff0000, v170
	v_lshlrev_b32_e32 v152, 16, v171
	v_and_b32_e32 v153, 0xffff0000, v171
	v_lshlrev_b32_e32 v154, 16, v172
	v_and_b32_e32 v155, 0xffff0000, v172
	v_lshlrev_b32_e32 v156, 16, v173
	v_and_b32_e32 v157, 0xffff0000, v173
	v_pk_mul_f32 v[126:127], v[126:127], v[150:151]
	v_pk_mul_f32 v[128:129], v[128:129], v[152:153]
	v_pk_mul_f32 v[122:123], v[122:123], v[154:155]
	v_pk_mul_f32 v[124:125], v[124:125], v[156:157]
	v_cvt_pk_bf16_f32 v170, v126, v127
	v_cvt_pk_bf16_f32 v171, v128, v129
	v_cvt_pk_bf16_f32 v172, v122, v123
	v_cvt_pk_bf16_f32 v173, v124, v125
	s_nop 1
	global_store_dwordx4 v134, v[170:173], s[26:27]
	v_pk_mul_f32 v[150:151], v[118:119], v[162:163]
	v_pk_mul_f32 v[152:153], v[120:121], v[162:163]
	v_pk_mul_f32 v[154:155], v[114:115], v[162:163]
	v_pk_mul_f32 v[156:157], v[116:117], v[162:163]
	v_exp_f32_e32 v150, v150
	v_exp_f32_e32 v151, v151
	v_exp_f32_e32 v152, v152
	v_exp_f32_e32 v153, v153
	v_exp_f32_e32 v154, v154
	v_exp_f32_e32 v155, v155
	v_exp_f32_e32 v156, v156
	v_exp_f32_e32 v157, v157
	v_pk_add_f32 v[150:151], v[150:151], v[164:165]
	v_pk_add_f32 v[152:153], v[152:153], v[164:165]
	v_pk_add_f32 v[154:155], v[154:155], v[164:165]
	v_pk_add_f32 v[156:157], v[156:157], v[164:165]
	v_rcp_f32_e32 v150, v150
	v_rcp_f32_e32 v151, v151
	v_rcp_f32_e32 v152, v152
	v_rcp_f32_e32 v153, v153
	v_rcp_f32_e32 v154, v154
	v_rcp_f32_e32 v155, v155
	v_rcp_f32_e32 v156, v156
	v_rcp_f32_e32 v157, v157
	v_pk_mul_f32 v[118:119], v[118:119], v[150:151]
	v_pk_mul_f32 v[120:121], v[120:121], v[152:153]
	v_pk_mul_f32 v[114:115], v[114:115], v[154:155]
	v_pk_mul_f32 v[116:117], v[116:117], v[156:157]
	s_waitcnt vmcnt(15)
	v_lshlrev_b32_e32 v150, 16, v174
	v_and_b32_e32 v151, 0xffff0000, v174
	v_lshlrev_b32_e32 v152, 16, v175
	v_and_b32_e32 v153, 0xffff0000, v175
	v_lshlrev_b32_e32 v154, 16, v176
	v_and_b32_e32 v155, 0xffff0000, v176
	v_lshlrev_b32_e32 v156, 16, v177
	v_and_b32_e32 v157, 0xffff0000, v177
	v_pk_mul_f32 v[118:119], v[118:119], v[150:151]
	v_pk_mul_f32 v[120:121], v[120:121], v[152:153]
	v_pk_mul_f32 v[114:115], v[114:115], v[154:155]
	v_pk_mul_f32 v[116:117], v[116:117], v[156:157]
	v_cvt_pk_bf16_f32 v174, v118, v119
	v_cvt_pk_bf16_f32 v175, v120, v121
	v_cvt_pk_bf16_f32 v176, v114, v115
	v_cvt_pk_bf16_f32 v177, v116, v117
	s_nop 1
	global_store_dwordx4 v134, v[174:177], s[26:27] offset:256
	v_pk_mul_f32 v[150:151], v[110:111], v[162:163]
	v_pk_mul_f32 v[152:153], v[112:113], v[162:163]
	v_pk_mul_f32 v[154:155], v[106:107], v[162:163]
	v_pk_mul_f32 v[156:157], v[108:109], v[162:163]
	v_exp_f32_e32 v150, v150
	v_exp_f32_e32 v151, v151
	v_exp_f32_e32 v152, v152
	v_exp_f32_e32 v153, v153
	v_exp_f32_e32 v154, v154
	v_exp_f32_e32 v155, v155
	v_exp_f32_e32 v156, v156
	v_exp_f32_e32 v157, v157
	v_pk_add_f32 v[150:151], v[150:151], v[164:165]
	v_pk_add_f32 v[152:153], v[152:153], v[164:165]
	v_pk_add_f32 v[154:155], v[154:155], v[164:165]
	v_pk_add_f32 v[156:157], v[156:157], v[164:165]
	v_rcp_f32_e32 v150, v150
	v_rcp_f32_e32 v151, v151
	v_rcp_f32_e32 v152, v152
	v_rcp_f32_e32 v153, v153
	v_rcp_f32_e32 v154, v154
	v_rcp_f32_e32 v155, v155
	v_rcp_f32_e32 v156, v156
	v_rcp_f32_e32 v157, v157
	v_pk_mul_f32 v[110:111], v[110:111], v[150:151]
	v_pk_mul_f32 v[112:113], v[112:113], v[152:153]
	v_pk_mul_f32 v[106:107], v[106:107], v[154:155]
	v_pk_mul_f32 v[108:109], v[108:109], v[156:157]
	s_waitcnt vmcnt(15)
	v_lshlrev_b32_e32 v150, 16, v178
	v_and_b32_e32 v151, 0xffff0000, v178
	v_lshlrev_b32_e32 v152, 16, v179
	v_and_b32_e32 v153, 0xffff0000, v179
	v_lshlrev_b32_e32 v154, 16, v180
	v_and_b32_e32 v155, 0xffff0000, v180
	v_lshlrev_b32_e32 v156, 16, v181
	v_and_b32_e32 v157, 0xffff0000, v181
	v_pk_mul_f32 v[110:111], v[110:111], v[150:151]
	v_pk_mul_f32 v[112:113], v[112:113], v[152:153]
	v_pk_mul_f32 v[106:107], v[106:107], v[154:155]
	v_pk_mul_f32 v[108:109], v[108:109], v[156:157]
	v_cvt_pk_bf16_f32 v178, v110, v111
	v_cvt_pk_bf16_f32 v179, v112, v113
	v_cvt_pk_bf16_f32 v180, v106, v107
	v_cvt_pk_bf16_f32 v181, v108, v109
	s_nop 1
	global_store_dwordx4 v135, v[178:181], s[26:27]
	v_pk_mul_f32 v[150:151], v[102:103], v[162:163]
	v_pk_mul_f32 v[152:153], v[104:105], v[162:163]
	v_pk_mul_f32 v[154:155], v[98:99], v[162:163]
	v_pk_mul_f32 v[156:157], v[100:101], v[162:163]
	v_exp_f32_e32 v150, v150
	v_exp_f32_e32 v151, v151
	v_exp_f32_e32 v152, v152
	v_exp_f32_e32 v153, v153
	v_exp_f32_e32 v154, v154
	v_exp_f32_e32 v155, v155
	v_exp_f32_e32 v156, v156
	v_exp_f32_e32 v157, v157
	v_pk_add_f32 v[150:151], v[150:151], v[164:165]
	v_pk_add_f32 v[152:153], v[152:153], v[164:165]
	v_pk_add_f32 v[154:155], v[154:155], v[164:165]
	v_pk_add_f32 v[156:157], v[156:157], v[164:165]
	v_rcp_f32_e32 v150, v150
	v_rcp_f32_e32 v151, v151
	v_rcp_f32_e32 v152, v152
	v_rcp_f32_e32 v153, v153
	v_rcp_f32_e32 v154, v154
	v_rcp_f32_e32 v155, v155
	v_rcp_f32_e32 v156, v156
	v_rcp_f32_e32 v157, v157
	v_pk_mul_f32 v[102:103], v[102:103], v[150:151]
	v_pk_mul_f32 v[104:105], v[104:105], v[152:153]
	v_pk_mul_f32 v[98:99], v[98:99], v[154:155]
	v_pk_mul_f32 v[100:101], v[100:101], v[156:157]
	s_waitcnt vmcnt(15)
	v_lshlrev_b32_e32 v150, 16, v182
	v_and_b32_e32 v151, 0xffff0000, v182
	v_lshlrev_b32_e32 v152, 16, v183
	v_and_b32_e32 v153, 0xffff0000, v183
	v_lshlrev_b32_e32 v154, 16, v184
	v_and_b32_e32 v155, 0xffff0000, v184
	v_lshlrev_b32_e32 v156, 16, v185
	v_and_b32_e32 v157, 0xffff0000, v185
	v_pk_mul_f32 v[102:103], v[102:103], v[150:151]
	v_pk_mul_f32 v[104:105], v[104:105], v[152:153]
	v_pk_mul_f32 v[98:99], v[98:99], v[154:155]
	v_pk_mul_f32 v[100:101], v[100:101], v[156:157]
	v_cvt_pk_bf16_f32 v182, v102, v103
	v_cvt_pk_bf16_f32 v183, v104, v105
	v_cvt_pk_bf16_f32 v184, v98, v99
	v_cvt_pk_bf16_f32 v185, v100, v101
	s_nop 1
	global_store_dwordx4 v135, v[182:185], s[26:27] offset:256
	v_pk_mul_f32 v[150:151], v[94:95], v[162:163]
	v_pk_mul_f32 v[152:153], v[96:97], v[162:163]
	v_pk_mul_f32 v[154:155], v[90:91], v[162:163]
	v_pk_mul_f32 v[156:157], v[92:93], v[162:163]
	v_exp_f32_e32 v150, v150
	v_exp_f32_e32 v151, v151
	v_exp_f32_e32 v152, v152
	v_exp_f32_e32 v153, v153
	v_exp_f32_e32 v154, v154
	v_exp_f32_e32 v155, v155
	v_exp_f32_e32 v156, v156
	v_exp_f32_e32 v157, v157
	v_pk_add_f32 v[150:151], v[150:151], v[164:165]
	v_pk_add_f32 v[152:153], v[152:153], v[164:165]
	v_pk_add_f32 v[154:155], v[154:155], v[164:165]
	v_pk_add_f32 v[156:157], v[156:157], v[164:165]
	v_rcp_f32_e32 v150, v150
	v_rcp_f32_e32 v151, v151
	v_rcp_f32_e32 v152, v152
	v_rcp_f32_e32 v153, v153
	v_rcp_f32_e32 v154, v154
	v_rcp_f32_e32 v155, v155
	v_rcp_f32_e32 v156, v156
	v_rcp_f32_e32 v157, v157
	v_pk_mul_f32 v[94:95], v[94:95], v[150:151]
	v_pk_mul_f32 v[96:97], v[96:97], v[152:153]
	v_pk_mul_f32 v[90:91], v[90:91], v[154:155]
	v_pk_mul_f32 v[92:93], v[92:93], v[156:157]
	s_waitcnt vmcnt(15)
	v_lshlrev_b32_e32 v150, 16, v186
	v_and_b32_e32 v151, 0xffff0000, v186
	v_lshlrev_b32_e32 v152, 16, v187
	v_and_b32_e32 v153, 0xffff0000, v187
	v_lshlrev_b32_e32 v154, 16, v188
	v_and_b32_e32 v155, 0xffff0000, v188
	v_lshlrev_b32_e32 v156, 16, v189
	v_and_b32_e32 v157, 0xffff0000, v189
	v_pk_mul_f32 v[94:95], v[94:95], v[150:151]
	v_pk_mul_f32 v[96:97], v[96:97], v[152:153]
	v_pk_mul_f32 v[90:91], v[90:91], v[154:155]
	v_pk_mul_f32 v[92:93], v[92:93], v[156:157]
	v_cvt_pk_bf16_f32 v186, v94, v95
	v_cvt_pk_bf16_f32 v187, v96, v97
	v_cvt_pk_bf16_f32 v188, v90, v91
	v_cvt_pk_bf16_f32 v189, v92, v93
	s_nop 1
	global_store_dwordx4 v136, v[186:189], s[26:27]
	v_pk_mul_f32 v[150:151], v[86:87], v[162:163]
	v_pk_mul_f32 v[152:153], v[88:89], v[162:163]
	v_pk_mul_f32 v[154:155], v[82:83], v[162:163]
	v_pk_mul_f32 v[156:157], v[84:85], v[162:163]
	v_exp_f32_e32 v150, v150
	v_exp_f32_e32 v151, v151
	v_exp_f32_e32 v152, v152
	v_exp_f32_e32 v153, v153
	v_exp_f32_e32 v154, v154
	v_exp_f32_e32 v155, v155
	v_exp_f32_e32 v156, v156
	v_exp_f32_e32 v157, v157
	v_pk_add_f32 v[150:151], v[150:151], v[164:165]
	v_pk_add_f32 v[152:153], v[152:153], v[164:165]
	v_pk_add_f32 v[154:155], v[154:155], v[164:165]
	v_pk_add_f32 v[156:157], v[156:157], v[164:165]
	v_rcp_f32_e32 v150, v150
	v_rcp_f32_e32 v151, v151
	v_rcp_f32_e32 v152, v152
	v_rcp_f32_e32 v153, v153
	v_rcp_f32_e32 v154, v154
	v_rcp_f32_e32 v155, v155
	v_rcp_f32_e32 v156, v156
	v_rcp_f32_e32 v157, v157
	v_pk_mul_f32 v[86:87], v[86:87], v[150:151]
	v_pk_mul_f32 v[88:89], v[88:89], v[152:153]
	v_pk_mul_f32 v[82:83], v[82:83], v[154:155]
	v_pk_mul_f32 v[84:85], v[84:85], v[156:157]
	s_waitcnt vmcnt(15)
	v_lshlrev_b32_e32 v150, 16, v190
	v_and_b32_e32 v151, 0xffff0000, v190
	v_lshlrev_b32_e32 v152, 16, v191
	v_and_b32_e32 v153, 0xffff0000, v191
	v_lshlrev_b32_e32 v154, 16, v192
	v_and_b32_e32 v155, 0xffff0000, v192
	v_lshlrev_b32_e32 v156, 16, v193
	v_and_b32_e32 v157, 0xffff0000, v193
	v_pk_mul_f32 v[86:87], v[86:87], v[150:151]
	v_pk_mul_f32 v[88:89], v[88:89], v[152:153]
	v_pk_mul_f32 v[82:83], v[82:83], v[154:155]
	v_pk_mul_f32 v[84:85], v[84:85], v[156:157]
	v_cvt_pk_bf16_f32 v190, v86, v87
	v_cvt_pk_bf16_f32 v191, v88, v89
	v_cvt_pk_bf16_f32 v192, v82, v83
	v_cvt_pk_bf16_f32 v193, v84, v85
	s_nop 1
	global_store_dwordx4 v136, v[190:193], s[26:27] offset:256
	v_pk_mul_f32 v[150:151], v[78:79], v[162:163]
	v_pk_mul_f32 v[152:153], v[80:81], v[162:163]
	v_pk_mul_f32 v[154:155], v[74:75], v[162:163]
	v_pk_mul_f32 v[156:157], v[76:77], v[162:163]
	v_exp_f32_e32 v150, v150
	v_exp_f32_e32 v151, v151
	v_exp_f32_e32 v152, v152
	v_exp_f32_e32 v153, v153
	v_exp_f32_e32 v154, v154
	v_exp_f32_e32 v155, v155
	v_exp_f32_e32 v156, v156
	v_exp_f32_e32 v157, v157
	v_pk_add_f32 v[150:151], v[150:151], v[164:165]
	v_pk_add_f32 v[152:153], v[152:153], v[164:165]
	v_pk_add_f32 v[154:155], v[154:155], v[164:165]
	v_pk_add_f32 v[156:157], v[156:157], v[164:165]
	v_rcp_f32_e32 v150, v150
	v_rcp_f32_e32 v151, v151
	v_rcp_f32_e32 v152, v152
	v_rcp_f32_e32 v153, v153
	v_rcp_f32_e32 v154, v154
	v_rcp_f32_e32 v155, v155
	v_rcp_f32_e32 v156, v156
	v_rcp_f32_e32 v157, v157
	v_pk_mul_f32 v[78:79], v[78:79], v[150:151]
	v_pk_mul_f32 v[80:81], v[80:81], v[152:153]
	v_pk_mul_f32 v[74:75], v[74:75], v[154:155]
	v_pk_mul_f32 v[76:77], v[76:77], v[156:157]
	s_waitcnt vmcnt(15)
	v_lshlrev_b32_e32 v150, 16, v194
	v_and_b32_e32 v151, 0xffff0000, v194
	v_lshlrev_b32_e32 v152, 16, v195
	v_and_b32_e32 v153, 0xffff0000, v195
	v_lshlrev_b32_e32 v154, 16, v196
	v_and_b32_e32 v155, 0xffff0000, v196
	v_lshlrev_b32_e32 v156, 16, v197
	v_and_b32_e32 v157, 0xffff0000, v197
	v_pk_mul_f32 v[78:79], v[78:79], v[150:151]
	v_pk_mul_f32 v[80:81], v[80:81], v[152:153]
	v_pk_mul_f32 v[74:75], v[74:75], v[154:155]
	v_pk_mul_f32 v[76:77], v[76:77], v[156:157]
	v_cvt_pk_bf16_f32 v194, v78, v79
	v_cvt_pk_bf16_f32 v195, v80, v81
	v_cvt_pk_bf16_f32 v196, v74, v75
	v_cvt_pk_bf16_f32 v197, v76, v77
	s_nop 1
	global_store_dwordx4 v137, v[194:197], s[26:27]
	v_pk_mul_f32 v[150:151], v[70:71], v[162:163]
	v_pk_mul_f32 v[152:153], v[72:73], v[162:163]
	v_pk_mul_f32 v[154:155], v[66:67], v[162:163]
	v_pk_mul_f32 v[156:157], v[68:69], v[162:163]
	v_exp_f32_e32 v150, v150
	v_exp_f32_e32 v151, v151
	v_exp_f32_e32 v152, v152
	v_exp_f32_e32 v153, v153
	v_exp_f32_e32 v154, v154
	v_exp_f32_e32 v155, v155
	v_exp_f32_e32 v156, v156
	v_exp_f32_e32 v157, v157
	v_pk_add_f32 v[150:151], v[150:151], v[164:165]
	v_pk_add_f32 v[152:153], v[152:153], v[164:165]
	v_pk_add_f32 v[154:155], v[154:155], v[164:165]
	v_pk_add_f32 v[156:157], v[156:157], v[164:165]
	v_rcp_f32_e32 v150, v150
	v_rcp_f32_e32 v151, v151
	v_rcp_f32_e32 v152, v152
	v_rcp_f32_e32 v153, v153
	v_rcp_f32_e32 v154, v154
	v_rcp_f32_e32 v155, v155
	v_rcp_f32_e32 v156, v156
	v_rcp_f32_e32 v157, v157
	v_pk_mul_f32 v[70:71], v[70:71], v[150:151]
	v_pk_mul_f32 v[72:73], v[72:73], v[152:153]
	v_pk_mul_f32 v[66:67], v[66:67], v[154:155]
	v_pk_mul_f32 v[68:69], v[68:69], v[156:157]
	s_waitcnt vmcnt(15)
	v_lshlrev_b32_e32 v150, 16, v198
	v_and_b32_e32 v151, 0xffff0000, v198
	v_lshlrev_b32_e32 v152, 16, v199
	v_and_b32_e32 v153, 0xffff0000, v199
	v_lshlrev_b32_e32 v154, 16, v200
	v_and_b32_e32 v155, 0xffff0000, v200
	v_lshlrev_b32_e32 v156, 16, v201
	v_and_b32_e32 v157, 0xffff0000, v201
	v_pk_mul_f32 v[70:71], v[70:71], v[150:151]
	v_pk_mul_f32 v[72:73], v[72:73], v[152:153]
	v_pk_mul_f32 v[66:67], v[66:67], v[154:155]
	v_pk_mul_f32 v[68:69], v[68:69], v[156:157]
	v_cvt_pk_bf16_f32 v198, v70, v71
	v_cvt_pk_bf16_f32 v199, v72, v73
	v_cvt_pk_bf16_f32 v200, v66, v67
	v_cvt_pk_bf16_f32 v201, v68, v69
	s_nop 1
	global_store_dwordx4 v137, v[198:201], s[26:27] offset:256
	v_pk_mul_f32 v[150:151], v[62:63], v[162:163]
	v_pk_mul_f32 v[152:153], v[64:65], v[162:163]
	v_pk_mul_f32 v[154:155], v[58:59], v[162:163]
	v_pk_mul_f32 v[156:157], v[60:61], v[162:163]
	v_exp_f32_e32 v150, v150
	v_exp_f32_e32 v151, v151
	v_exp_f32_e32 v152, v152
	v_exp_f32_e32 v153, v153
	v_exp_f32_e32 v154, v154
	v_exp_f32_e32 v155, v155
	v_exp_f32_e32 v156, v156
	v_exp_f32_e32 v157, v157
	v_pk_add_f32 v[150:151], v[150:151], v[164:165]
	v_pk_add_f32 v[152:153], v[152:153], v[164:165]
	v_pk_add_f32 v[154:155], v[154:155], v[164:165]
	v_pk_add_f32 v[156:157], v[156:157], v[164:165]
	v_rcp_f32_e32 v150, v150
	v_rcp_f32_e32 v151, v151
	v_rcp_f32_e32 v152, v152
	v_rcp_f32_e32 v153, v153
	v_rcp_f32_e32 v154, v154
	v_rcp_f32_e32 v155, v155
	v_rcp_f32_e32 v156, v156
	v_rcp_f32_e32 v157, v157
	v_pk_mul_f32 v[62:63], v[62:63], v[150:151]
	v_pk_mul_f32 v[64:65], v[64:65], v[152:153]
	v_pk_mul_f32 v[58:59], v[58:59], v[154:155]
	v_pk_mul_f32 v[60:61], v[60:61], v[156:157]
	s_waitcnt vmcnt(15)
	v_lshlrev_b32_e32 v150, 16, v202
	v_and_b32_e32 v151, 0xffff0000, v202
	v_lshlrev_b32_e32 v152, 16, v203
	v_and_b32_e32 v153, 0xffff0000, v203
	v_lshlrev_b32_e32 v154, 16, v204
	v_and_b32_e32 v155, 0xffff0000, v204
	v_lshlrev_b32_e32 v156, 16, v205
	v_and_b32_e32 v157, 0xffff0000, v205
	v_pk_mul_f32 v[62:63], v[62:63], v[150:151]
	v_pk_mul_f32 v[64:65], v[64:65], v[152:153]
	v_pk_mul_f32 v[58:59], v[58:59], v[154:155]
	v_pk_mul_f32 v[60:61], v[60:61], v[156:157]
	v_cvt_pk_bf16_f32 v202, v62, v63
	v_cvt_pk_bf16_f32 v203, v64, v65
	v_cvt_pk_bf16_f32 v204, v58, v59
	v_cvt_pk_bf16_f32 v205, v60, v61
	s_nop 1
	global_store_dwordx4 v158, v[202:205], s[26:27]
	v_pk_mul_f32 v[150:151], v[54:55], v[162:163]
	v_pk_mul_f32 v[152:153], v[56:57], v[162:163]
	v_pk_mul_f32 v[154:155], v[50:51], v[162:163]
	v_pk_mul_f32 v[156:157], v[52:53], v[162:163]
	v_exp_f32_e32 v150, v150
	v_exp_f32_e32 v151, v151
	v_exp_f32_e32 v152, v152
	v_exp_f32_e32 v153, v153
	v_exp_f32_e32 v154, v154
	v_exp_f32_e32 v155, v155
	v_exp_f32_e32 v156, v156
	v_exp_f32_e32 v157, v157
	v_pk_add_f32 v[150:151], v[150:151], v[164:165]
	v_pk_add_f32 v[152:153], v[152:153], v[164:165]
	v_pk_add_f32 v[154:155], v[154:155], v[164:165]
	v_pk_add_f32 v[156:157], v[156:157], v[164:165]
	v_rcp_f32_e32 v150, v150
	v_rcp_f32_e32 v151, v151
	v_rcp_f32_e32 v152, v152
	v_rcp_f32_e32 v153, v153
	v_rcp_f32_e32 v154, v154
	v_rcp_f32_e32 v155, v155
	v_rcp_f32_e32 v156, v156
	v_rcp_f32_e32 v157, v157
	v_pk_mul_f32 v[54:55], v[54:55], v[150:151]
	v_pk_mul_f32 v[56:57], v[56:57], v[152:153]
	v_pk_mul_f32 v[50:51], v[50:51], v[154:155]
	v_pk_mul_f32 v[52:53], v[52:53], v[156:157]
	s_waitcnt vmcnt(15)
	v_lshlrev_b32_e32 v150, 16, v206
	v_and_b32_e32 v151, 0xffff0000, v206
	v_lshlrev_b32_e32 v152, 16, v207
	v_and_b32_e32 v153, 0xffff0000, v207
	v_lshlrev_b32_e32 v154, 16, v208
	v_and_b32_e32 v155, 0xffff0000, v208
	v_lshlrev_b32_e32 v156, 16, v209
	v_and_b32_e32 v157, 0xffff0000, v209
	v_pk_mul_f32 v[54:55], v[54:55], v[150:151]
	v_pk_mul_f32 v[56:57], v[56:57], v[152:153]
	v_pk_mul_f32 v[50:51], v[50:51], v[154:155]
	v_pk_mul_f32 v[52:53], v[52:53], v[156:157]
	v_cvt_pk_bf16_f32 v206, v54, v55
	v_cvt_pk_bf16_f32 v207, v56, v57
	v_cvt_pk_bf16_f32 v208, v50, v51
	v_cvt_pk_bf16_f32 v209, v52, v53
	s_nop 1
	global_store_dwordx4 v158, v[206:209], s[26:27] offset:256
	v_pk_mul_f32 v[150:151], v[46:47], v[162:163]
	v_pk_mul_f32 v[152:153], v[48:49], v[162:163]
	v_pk_mul_f32 v[154:155], v[42:43], v[162:163]
	v_pk_mul_f32 v[156:157], v[44:45], v[162:163]
	v_exp_f32_e32 v150, v150
	v_exp_f32_e32 v151, v151
	v_exp_f32_e32 v152, v152
	v_exp_f32_e32 v153, v153
	v_exp_f32_e32 v154, v154
	v_exp_f32_e32 v155, v155
	v_exp_f32_e32 v156, v156
	v_exp_f32_e32 v157, v157
	v_pk_add_f32 v[150:151], v[150:151], v[164:165]
	v_pk_add_f32 v[152:153], v[152:153], v[164:165]
	v_pk_add_f32 v[154:155], v[154:155], v[164:165]
	v_pk_add_f32 v[156:157], v[156:157], v[164:165]
	v_rcp_f32_e32 v150, v150
	v_rcp_f32_e32 v151, v151
	v_rcp_f32_e32 v152, v152
	v_rcp_f32_e32 v153, v153
	v_rcp_f32_e32 v154, v154
	v_rcp_f32_e32 v155, v155
	v_rcp_f32_e32 v156, v156
	v_rcp_f32_e32 v157, v157
	v_pk_mul_f32 v[46:47], v[46:47], v[150:151]
	v_pk_mul_f32 v[48:49], v[48:49], v[152:153]
	v_pk_mul_f32 v[42:43], v[42:43], v[154:155]
	v_pk_mul_f32 v[44:45], v[44:45], v[156:157]
	s_waitcnt vmcnt(15)
	v_lshlrev_b32_e32 v150, 16, v224
	v_and_b32_e32 v151, 0xffff0000, v224
	v_lshlrev_b32_e32 v152, 16, v225
	v_and_b32_e32 v153, 0xffff0000, v225
	v_lshlrev_b32_e32 v154, 16, v226
	v_and_b32_e32 v155, 0xffff0000, v226
	v_lshlrev_b32_e32 v156, 16, v227
	v_and_b32_e32 v157, 0xffff0000, v227
	v_pk_mul_f32 v[46:47], v[46:47], v[150:151]
	v_pk_mul_f32 v[48:49], v[48:49], v[152:153]
	v_pk_mul_f32 v[42:43], v[42:43], v[154:155]
	v_pk_mul_f32 v[44:45], v[44:45], v[156:157]
	v_cvt_pk_bf16_f32 v224, v46, v47
	v_cvt_pk_bf16_f32 v225, v48, v49
	v_cvt_pk_bf16_f32 v226, v42, v43
	v_cvt_pk_bf16_f32 v227, v44, v45
	s_nop 1
	global_store_dwordx4 v159, v[224:227], s[26:27]
	v_pk_mul_f32 v[150:151], v[38:39], v[162:163]
	v_pk_mul_f32 v[152:153], v[40:41], v[162:163]
	v_pk_mul_f32 v[154:155], v[34:35], v[162:163]
	v_pk_mul_f32 v[156:157], v[36:37], v[162:163]
	v_exp_f32_e32 v150, v150
	v_exp_f32_e32 v151, v151
	v_exp_f32_e32 v152, v152
	v_exp_f32_e32 v153, v153
	v_exp_f32_e32 v154, v154
	v_exp_f32_e32 v155, v155
	v_exp_f32_e32 v156, v156
	v_exp_f32_e32 v157, v157
	v_pk_add_f32 v[150:151], v[150:151], v[164:165]
	v_pk_add_f32 v[152:153], v[152:153], v[164:165]
	v_pk_add_f32 v[154:155], v[154:155], v[164:165]
	v_pk_add_f32 v[156:157], v[156:157], v[164:165]
	v_rcp_f32_e32 v150, v150
	v_rcp_f32_e32 v151, v151
	v_rcp_f32_e32 v152, v152
	v_rcp_f32_e32 v153, v153
	v_rcp_f32_e32 v154, v154
	v_rcp_f32_e32 v155, v155
	v_rcp_f32_e32 v156, v156
	v_rcp_f32_e32 v157, v157
	v_pk_mul_f32 v[38:39], v[38:39], v[150:151]
	v_pk_mul_f32 v[40:41], v[40:41], v[152:153]
	v_pk_mul_f32 v[34:35], v[34:35], v[154:155]
	v_pk_mul_f32 v[36:37], v[36:37], v[156:157]
	s_waitcnt vmcnt(15)
	v_lshlrev_b32_e32 v150, 16, v228
	v_and_b32_e32 v151, 0xffff0000, v228
	v_lshlrev_b32_e32 v152, 16, v229
	v_and_b32_e32 v153, 0xffff0000, v229
	v_lshlrev_b32_e32 v154, 16, v230
	v_and_b32_e32 v155, 0xffff0000, v230
	v_lshlrev_b32_e32 v156, 16, v231
	v_and_b32_e32 v157, 0xffff0000, v231
	v_pk_mul_f32 v[38:39], v[38:39], v[150:151]
	v_pk_mul_f32 v[40:41], v[40:41], v[152:153]
	v_pk_mul_f32 v[34:35], v[34:35], v[154:155]
	v_pk_mul_f32 v[36:37], v[36:37], v[156:157]
	v_cvt_pk_bf16_f32 v228, v38, v39
	v_cvt_pk_bf16_f32 v229, v40, v41
	v_cvt_pk_bf16_f32 v230, v34, v35
	v_cvt_pk_bf16_f32 v231, v36, v37
	s_nop 1
	global_store_dwordx4 v159, v[228:231], s[26:27] offset:256
	v_pk_mul_f32 v[150:151], v[30:31], v[162:163]
	v_pk_mul_f32 v[152:153], v[32:33], v[162:163]
	v_pk_mul_f32 v[154:155], v[26:27], v[162:163]
	v_pk_mul_f32 v[156:157], v[28:29], v[162:163]
	v_exp_f32_e32 v150, v150
	v_exp_f32_e32 v151, v151
	v_exp_f32_e32 v152, v152
	v_exp_f32_e32 v153, v153
	v_exp_f32_e32 v154, v154
	v_exp_f32_e32 v155, v155
	v_exp_f32_e32 v156, v156
	v_exp_f32_e32 v157, v157
	v_pk_add_f32 v[150:151], v[150:151], v[164:165]
	v_pk_add_f32 v[152:153], v[152:153], v[164:165]
	v_pk_add_f32 v[154:155], v[154:155], v[164:165]
	v_pk_add_f32 v[156:157], v[156:157], v[164:165]
	v_rcp_f32_e32 v150, v150
	v_rcp_f32_e32 v151, v151
	v_rcp_f32_e32 v152, v152
	v_rcp_f32_e32 v153, v153
	v_rcp_f32_e32 v154, v154
	v_rcp_f32_e32 v155, v155
	v_rcp_f32_e32 v156, v156
	v_rcp_f32_e32 v157, v157
	v_pk_mul_f32 v[30:31], v[30:31], v[150:151]
	v_pk_mul_f32 v[32:33], v[32:33], v[152:153]
	v_pk_mul_f32 v[26:27], v[26:27], v[154:155]
	v_pk_mul_f32 v[28:29], v[28:29], v[156:157]
	s_waitcnt vmcnt(15)
	v_lshlrev_b32_e32 v150, 16, v232
	v_and_b32_e32 v151, 0xffff0000, v232
	v_lshlrev_b32_e32 v152, 16, v233
	v_and_b32_e32 v153, 0xffff0000, v233
	v_lshlrev_b32_e32 v154, 16, v234
	v_and_b32_e32 v155, 0xffff0000, v234
	v_lshlrev_b32_e32 v156, 16, v235
	v_and_b32_e32 v157, 0xffff0000, v235
	v_pk_mul_f32 v[30:31], v[30:31], v[150:151]
	v_pk_mul_f32 v[32:33], v[32:33], v[152:153]
	v_pk_mul_f32 v[26:27], v[26:27], v[154:155]
	v_pk_mul_f32 v[28:29], v[28:29], v[156:157]
	v_cvt_pk_bf16_f32 v232, v30, v31
	v_cvt_pk_bf16_f32 v233, v32, v33
	v_cvt_pk_bf16_f32 v234, v26, v27
	v_cvt_pk_bf16_f32 v235, v28, v29
	s_nop 1
	global_store_dwordx4 v160, v[232:235], s[26:27]
	v_pk_mul_f32 v[150:151], v[22:23], v[162:163]
	v_pk_mul_f32 v[152:153], v[24:25], v[162:163]
	v_pk_mul_f32 v[154:155], v[18:19], v[162:163]
	v_pk_mul_f32 v[156:157], v[20:21], v[162:163]
	v_exp_f32_e32 v150, v150
	v_exp_f32_e32 v151, v151
	v_exp_f32_e32 v152, v152
	v_exp_f32_e32 v153, v153
	v_exp_f32_e32 v154, v154
	v_exp_f32_e32 v155, v155
	v_exp_f32_e32 v156, v156
	v_exp_f32_e32 v157, v157
	v_pk_add_f32 v[150:151], v[150:151], v[164:165]
	v_pk_add_f32 v[152:153], v[152:153], v[164:165]
	v_pk_add_f32 v[154:155], v[154:155], v[164:165]
	v_pk_add_f32 v[156:157], v[156:157], v[164:165]
	v_rcp_f32_e32 v150, v150
	v_rcp_f32_e32 v151, v151
	v_rcp_f32_e32 v152, v152
	v_rcp_f32_e32 v153, v153
	v_rcp_f32_e32 v154, v154
	v_rcp_f32_e32 v155, v155
	v_rcp_f32_e32 v156, v156
	v_rcp_f32_e32 v157, v157
	v_pk_mul_f32 v[22:23], v[22:23], v[150:151]
	v_pk_mul_f32 v[24:25], v[24:25], v[152:153]
	v_pk_mul_f32 v[18:19], v[18:19], v[154:155]
	v_pk_mul_f32 v[20:21], v[20:21], v[156:157]
	s_waitcnt vmcnt(15)
	v_lshlrev_b32_e32 v150, 16, v236
	v_and_b32_e32 v151, 0xffff0000, v236
	v_lshlrev_b32_e32 v152, 16, v237
	v_and_b32_e32 v153, 0xffff0000, v237
	v_lshlrev_b32_e32 v154, 16, v238
	v_and_b32_e32 v155, 0xffff0000, v238
	v_lshlrev_b32_e32 v156, 16, v239
	v_and_b32_e32 v157, 0xffff0000, v239
	v_pk_mul_f32 v[22:23], v[22:23], v[150:151]
	v_pk_mul_f32 v[24:25], v[24:25], v[152:153]
	v_pk_mul_f32 v[18:19], v[18:19], v[154:155]
	v_pk_mul_f32 v[20:21], v[20:21], v[156:157]
	v_cvt_pk_bf16_f32 v236, v22, v23
	v_cvt_pk_bf16_f32 v237, v24, v25
	v_cvt_pk_bf16_f32 v238, v18, v19
	v_cvt_pk_bf16_f32 v239, v20, v21
	s_nop 1
	global_store_dwordx4 v160, v[236:239], s[26:27] offset:256
	v_pk_mul_f32 v[150:151], v[14:15], v[162:163]
	v_pk_mul_f32 v[152:153], v[16:17], v[162:163]
	v_pk_mul_f32 v[154:155], v[10:11], v[162:163]
	v_pk_mul_f32 v[156:157], v[12:13], v[162:163]
	v_exp_f32_e32 v150, v150
	v_exp_f32_e32 v151, v151
	v_exp_f32_e32 v152, v152
	v_exp_f32_e32 v153, v153
	v_exp_f32_e32 v154, v154
	v_exp_f32_e32 v155, v155
	v_exp_f32_e32 v156, v156
	v_exp_f32_e32 v157, v157
	v_pk_add_f32 v[150:151], v[150:151], v[164:165]
	v_pk_add_f32 v[152:153], v[152:153], v[164:165]
	v_pk_add_f32 v[154:155], v[154:155], v[164:165]
	v_pk_add_f32 v[156:157], v[156:157], v[164:165]
	v_rcp_f32_e32 v150, v150
	v_rcp_f32_e32 v151, v151
	v_rcp_f32_e32 v152, v152
	v_rcp_f32_e32 v153, v153
	v_rcp_f32_e32 v154, v154
	v_rcp_f32_e32 v155, v155
	v_rcp_f32_e32 v156, v156
	v_rcp_f32_e32 v157, v157
	v_pk_mul_f32 v[14:15], v[14:15], v[150:151]
	v_pk_mul_f32 v[16:17], v[16:17], v[152:153]
	v_pk_mul_f32 v[10:11], v[10:11], v[154:155]
	v_pk_mul_f32 v[12:13], v[12:13], v[156:157]
	s_waitcnt vmcnt(15)
	v_lshlrev_b32_e32 v150, 16, v240
	v_and_b32_e32 v151, 0xffff0000, v240
	v_lshlrev_b32_e32 v152, 16, v241
	v_and_b32_e32 v153, 0xffff0000, v241
	v_lshlrev_b32_e32 v154, 16, v242
	v_and_b32_e32 v155, 0xffff0000, v242
	v_lshlrev_b32_e32 v156, 16, v243
	v_and_b32_e32 v157, 0xffff0000, v243
	v_pk_mul_f32 v[14:15], v[14:15], v[150:151]
	v_pk_mul_f32 v[16:17], v[16:17], v[152:153]
	v_pk_mul_f32 v[10:11], v[10:11], v[154:155]
	v_pk_mul_f32 v[12:13], v[12:13], v[156:157]
	v_cvt_pk_bf16_f32 v240, v14, v15
	v_cvt_pk_bf16_f32 v241, v16, v17
	v_cvt_pk_bf16_f32 v242, v10, v11
	v_cvt_pk_bf16_f32 v243, v12, v13
	s_nop 1
	global_store_dwordx4 v161, v[240:243], s[26:27]
	v_pk_mul_f32 v[150:151], v[6:7], v[162:163]
	v_pk_mul_f32 v[152:153], v[8:9], v[162:163]
	v_pk_mul_f32 v[154:155], v[2:3], v[162:163]
	v_pk_mul_f32 v[156:157], v[4:5], v[162:163]
	v_exp_f32_e32 v150, v150
	v_exp_f32_e32 v151, v151
	v_exp_f32_e32 v152, v152
	v_exp_f32_e32 v153, v153
	v_exp_f32_e32 v154, v154
	v_exp_f32_e32 v155, v155
	v_exp_f32_e32 v156, v156
	v_exp_f32_e32 v157, v157
	v_pk_add_f32 v[150:151], v[150:151], v[164:165]
	v_pk_add_f32 v[152:153], v[152:153], v[164:165]
	v_pk_add_f32 v[154:155], v[154:155], v[164:165]
	v_pk_add_f32 v[156:157], v[156:157], v[164:165]
	v_rcp_f32_e32 v150, v150
	v_rcp_f32_e32 v151, v151
	v_rcp_f32_e32 v152, v152
	v_rcp_f32_e32 v153, v153
	v_rcp_f32_e32 v154, v154
	v_rcp_f32_e32 v155, v155
	v_rcp_f32_e32 v156, v156
	v_rcp_f32_e32 v157, v157
	v_pk_mul_f32 v[6:7], v[6:7], v[150:151]
	v_pk_mul_f32 v[8:9], v[8:9], v[152:153]
	v_pk_mul_f32 v[2:3], v[2:3], v[154:155]
	v_pk_mul_f32 v[4:5], v[4:5], v[156:157]
	s_waitcnt vmcnt(15)
	v_lshlrev_b32_e32 v150, 16, v244
	v_and_b32_e32 v151, 0xffff0000, v244
	v_lshlrev_b32_e32 v152, 16, v245
	v_and_b32_e32 v153, 0xffff0000, v245
	v_lshlrev_b32_e32 v154, 16, v246
	v_and_b32_e32 v155, 0xffff0000, v246
	v_lshlrev_b32_e32 v156, 16, v247
	v_and_b32_e32 v157, 0xffff0000, v247
	v_pk_mul_f32 v[6:7], v[6:7], v[150:151]
	v_pk_mul_f32 v[8:9], v[8:9], v[152:153]
	v_pk_mul_f32 v[2:3], v[2:3], v[154:155]
	v_pk_mul_f32 v[4:5], v[4:5], v[156:157]
	v_cvt_pk_bf16_f32 v244, v6, v7
	v_cvt_pk_bf16_f32 v245, v8, v9
	v_cvt_pk_bf16_f32 v246, v2, v3
	v_cvt_pk_bf16_f32 v247, v4, v5
	s_nop 1
	global_store_dwordx4 v161, v[244:247], s[26:27] offset:256
	s_andn2_b64 vcc, exec, s[4:5]
	s_mov_b64 s[4:5], -1
	s_cbranch_vccnz .LBB0_1455
